# GU epilogue: 8 ssq loads issued together (was 7 serialized round trips per tile); shw_reduce: 16 partial loads in flight then same fixed-order sum (on top of scan + in-proj epilogue head)
# speedup vs baseline: 1.0145x; 1.0145x over previous
; __device__ __forceinline__ unsigned cvt_pk_bf16(float lo, float hi) { unsigned r; asm volatile("v_cvt_pk_bf16_f32 %0, %1, %2" : "=v"(r) : "v"(lo), "v"(hi)); return r; }
; #define GAS __attribute__((address_space(1)))
;     __device__ __forceinline__ void operator()(const f32x4 (&acc)[2][2][4][2], const pg8::Unit& u, int wr, int wc, int fr, int fq) const {
;         f32x4 sh[2][2];
; #pragma unroll
;         for (int bj = 0; bj < 2; ++bj)
; #pragma unroll
;             for (int n = 0; n < 2; ++n) sh[bj][n] = *(const GAS f32x4*)(shW + 256 * u.pn + 128 * bj + 32 * wc + 8 * fq + 4 * n);
;         const int row0 = 256 * u.pm + 64 * wr + fr;
;         float rs[2][4];
; #pragma unroll
;         for (int ai = 0; ai < 2; ++ai)
; #pragma unroll
;             for (int m = 0; m < 4; ++m) rs[ai][m] = (float)ssq[row0 + 128 * ai + 16 * m] * (1.0f / 1024.0f);
; #pragma unroll
;         for (int ai = 0; ai < 2; ++ai)
; #pragma unroll
;             for (int m = 0; m < 4; ++m) {
;                 const int row = row0 + 128 * ai + 16 * m;
;                 const float rstd = __builtin_amdgcn_rsqf(rs[ai][m] * (1.0f / DM) + EPSF);
;                 f32x4 o[2];
; #pragma unroll
;                 for (int n = 0; n < 2; ++n) {
;                     const f32x4 g = acc[ai][0][m][n] * rstd + sh[0][n], uu = acc[ai][1][m][n] * rstd + sh[1][n];
; #pragma unroll
;                     for (int h = 0; h < 2; ++h) {
;                         const f32x2 g2 = {g[2 * h], g[2 * h + 1]}, u2 = {uu[2 * h], uu[2 * h + 1]};
;                         const f32x2 t = g2 * (-1.4426950408889634f);
;                         f32x2 e; e.x = __builtin_amdgcn_exp2f(t.x); e.y = __builtin_amdgcn_exp2f(t.y);
;                         const f32x2 d = e + 1.0f;
;                         f32x2 r; r.x = __builtin_amdgcn_rcpf(d.x); r.y = __builtin_amdgcn_rcpf(d.y);
;                         const f32x2 p = (g2 * u2) * r;
;                         o[n][2 * h] = p.x; o[n][2 * h + 1] = p.y;
;                     }
;                 }
;                 u32x4 w; w.x = cvt_pk_bf16(o[0][0], o[0][1]); w.y = cvt_pk_bf16(o[0][2], o[0][3]); w.z = cvt_pk_bf16(o[1][0], o[1][1]); w.w = cvt_pk_bf16(o[1][2], o[1][3]);
;                 *(GAS u32x4*)(act + (((size_t)u.pm * (FH / 64) + 2 * u.pn + (wc >> 1)) * 256 + (row - 256 * u.pm)) * 64 + 32 * (wc & 1) + 8 * fq) = w;
.LBB0_169:
	s_lshl_b32 s52, s18, 8
	v_lshl_add_u32 v180, s28, 8, v154
	s_ashr_i32 s53, s52, 31
	v_ashrrev_i32_e32 v181, 31, v180
	v_lshl_add_u64 v[78:79], s[52:53], 2, v[172:173]
	v_lshl_add_u64 v[180:181], v[180:181], 2, s[4:5]
	global_load_dwordx4 v[70:73], v[78:79], off offset:16
	global_load_dwordx4 v[82:85], v[78:79], off
	global_load_dwordx4 v[66:69], v[78:79], off offset:528
	s_nop 0
	global_load_dwordx4 v[78:81], v[78:79], off offset:512
	s_lshl_b32 s18, s18, 1
	global_load_dword v182, v[180:181], off
	global_load_dword v192, v[180:181], off offset:64
	global_load_dword v191, v[180:181], off offset:128
	global_load_dword v190, v[180:181], off offset:192
	global_load_dword v189, v[180:181], off offset:512
	global_load_dword v188, v[180:181], off offset:576
	global_load_dword v187, v[180:181], off offset:640
	global_load_dword v186, v[180:181], off offset:704
	s_mul_i32 s15, s28, 44
	s_ashr_i32 s19, s18, 31
	s_mul_hi_i32 s13, s28, 44
	s_add_u32 s18, s15, s18
	s_addc_u32 s19, s13, s19
	s_or_b64 s[18:19], s[18:19], s[10:11]
	s_lshl_b64 s[28:29], s[18:19], 15
	s_mov_b32 s18, 0xbfb8aa3b
	s_add_u32 s28, s94, s28
	s_addc_u32 s29, s95, s29
	s_andn2_b64 vcc, exec, s[0:1]
	v_readlane_b32 s77, v254, 50
	v_mov_b64_e32 v[220:221], v[230:231]
	v_mov_b64_e32 v[222:223], v[234:235]
	v_mov_b32_e32 v224, v236
	v_mov_b32_e32 v225, v237
	v_mov_b32_e32 v226, v246
	s_waitcnt vmcnt(0)
	v_cvt_f32_u32_e32 v182, v182
	v_cvt_f32_u32_e32 v192, v192
	v_cvt_f32_u32_e32 v191, v191
	v_cvt_f32_u32_e32 v190, v190
	v_cvt_f32_u32_e32 v189, v189
	v_cvt_f32_u32_e32 v188, v188
	v_cvt_f32_u32_e32 v187, v187
	v_cvt_f32_u32_e32 v186, v186
	v_mul_f32_e32 v182, 0x3a800000, v182
	v_mul_f32_e32 v192, 0x3a800000, v192
	v_mul_f32_e32 v191, 0x3a800000, v191
	v_mul_f32_e32 v190, 0x3a800000, v190
	v_mul_f32_e32 v189, 0x3a800000, v189
	v_mul_f32_e32 v188, 0x3a800000, v188
	v_mul_f32_e32 v187, 0x3a800000, v187
	v_mul_f32_e32 v186, 0x3a800000, v186
	v_fmamk_f32 v180, v182, 0x3a800000, v233
	v_rsq_f32_e32 v180, v180
	s_nop 0
	v_pk_fma_f32 v[144:145], v[144:145], v[180:181], v[84:85] op_sel_hi:[1,0,1]
	v_pk_fma_f32 v[142:143], v[142:143], v[180:181], v[82:83] op_sel_hi:[1,0,1]
	v_pk_fma_f32 v[134:135], v[134:135], v[180:181], v[78:79] op_sel_hi:[1,0,1]
	v_pk_mul_f32 v[182:183], v[142:143], s[18:19] op_sel_hi:[1,0]
	v_pk_mul_f32 v[134:135], v[142:143], v[134:135]
	v_pk_mul_f32 v[142:143], v[144:145], s[18:19] op_sel_hi:[1,0]
	v_pk_fma_f32 v[136:137], v[136:137], v[180:181], v[80:81] op_sel_hi:[1,0,1]
	v_exp_f32_e32 v142, v142
	v_exp_f32_e32 v143, v143
	v_pk_mul_f32 v[136:137], v[144:145], v[136:137]
	v_pk_fma_f32 v[138:139], v[138:139], v[180:181], v[70:71] op_sel_hi:[1,0,1]
	v_pk_fma_f32 v[130:131], v[130:131], v[180:181], v[66:67] op_sel_hi:[1,0,1]
	v_pk_add_f32 v[142:143], v[142:143], 1.0 op_sel_hi:[1,0]
	v_pk_fma_f32 v[140:141], v[140:141], v[180:181], v[72:73] op_sel_hi:[1,0,1]
	v_rcp_f32_e32 v142, v142
	v_rcp_f32_e32 v143, v143
	v_pk_mul_f32 v[130:131], v[138:139], v[130:131]
	v_exp_f32_e32 v182, v182
	v_exp_f32_e32 v183, v183
	v_pk_mul_f32 v[136:137], v[136:137], v[142:143]
	v_pk_mul_f32 v[142:143], v[138:139], s[18:19] op_sel_hi:[1,0]
	v_pk_fma_f32 v[132:133], v[132:133], v[180:181], v[68:69] op_sel_hi:[1,0,1]
	v_exp_f32_e32 v142, v142
	v_exp_f32_e32 v143, v143
	v_pk_add_f32 v[182:183], v[182:183], 1.0 op_sel_hi:[1,0]
	v_pk_mul_f32 v[132:133], v[140:141], v[132:133]
	v_rcp_f32_e32 v182, v182
	v_pk_add_f32 v[142:143], v[142:143], 1.0 op_sel_hi:[1,0]
	v_rcp_f32_e32 v183, v183
	v_rcp_f32_e32 v142, v142
	v_rcp_f32_e32 v143, v143
	v_pk_mul_f32 v[134:135], v[134:135], v[182:183]
	v_pk_mul_f32 v[138:139], v[130:131], v[142:143]
	v_pk_mul_f32 v[130:131], v[140:141], s[18:19] op_sel_hi:[1,0]
	s_nop 0
	v_exp_f32_e32 v130, v130
	v_exp_f32_e32 v131, v131
	s_nop 0
	v_pk_add_f32 v[130:131], v[130:131], 1.0 op_sel_hi:[1,0]
	s_nop 0
	v_rcp_f32_e32 v130, v130
	v_rcp_f32_e32 v131, v131
	s_nop 0
	v_pk_mul_f32 v[140:141], v[132:133], v[130:131]
	v_cvt_pk_bf16_f32 v130, v134, v135
	v_lshl_add_u64 v[134:135], s[28:29], 0, v[156:157]
	v_lshl_add_u64 v[134:135], v[134:135], 0, s[30:31]
	v_lshl_add_u64 v[134:135], v[134:135], 0, v[178:179]
	v_cvt_pk_bf16_f32 v131, v136, v137
	v_cvt_pk_bf16_f32 v132, v138, v139
	v_cvt_pk_bf16_f32 v133, v140, v141
	global_store_dwordx4 v[134:135], v[130:133], off
	s_nop 1
	v_fmamk_f32 v130, v192, 0x3a800000, v233
	v_rsq_f32_e32 v130, v130
	s_nop 0
	v_pk_fma_f32 v[128:129], v[128:129], v[130:131], v[84:85] op_sel_hi:[1,0,1]
	v_pk_fma_f32 v[126:127], v[126:127], v[130:131], v[82:83] op_sel_hi:[1,0,1]
	v_pk_fma_f32 v[122:123], v[122:123], v[130:131], v[78:79] op_sel_hi:[1,0,1]
	v_pk_mul_f32 v[132:133], v[126:127], s[18:19] op_sel_hi:[1,0]
	v_pk_mul_f32 v[122:123], v[126:127], v[122:123]
	v_pk_mul_f32 v[126:127], v[128:129], s[18:19] op_sel_hi:[1,0]
	v_pk_fma_f32 v[124:125], v[124:125], v[130:131], v[80:81] op_sel_hi:[1,0,1]
	v_exp_f32_e32 v126, v126
	v_exp_f32_e32 v127, v127
	v_pk_mul_f32 v[124:125], v[128:129], v[124:125]
	v_pk_fma_f32 v[118:119], v[118:119], v[130:131], v[70:71] op_sel_hi:[1,0,1]
	v_pk_fma_f32 v[114:115], v[114:115], v[130:131], v[66:67] op_sel_hi:[1,0,1]
	v_pk_add_f32 v[126:127], v[126:127], 1.0 op_sel_hi:[1,0]
	v_pk_fma_f32 v[120:121], v[120:121], v[130:131], v[72:73] op_sel_hi:[1,0,1]
	v_rcp_f32_e32 v126, v126
	v_rcp_f32_e32 v127, v127
	v_pk_mul_f32 v[114:115], v[118:119], v[114:115]
	v_exp_f32_e32 v132, v132
	v_exp_f32_e32 v133, v133
	v_pk_mul_f32 v[124:125], v[124:125], v[126:127]
	v_pk_mul_f32 v[126:127], v[118:119], s[18:19] op_sel_hi:[1,0]
	v_pk_fma_f32 v[116:117], v[116:117], v[130:131], v[68:69] op_sel_hi:[1,0,1]
	v_exp_f32_e32 v126, v126
; __device__ __forceinline__ unsigned cvt_pk_bf16(float lo, float hi) { unsigned r; asm volatile("v_cvt_pk_bf16_f32 %0, %1, %2" : "=v"(r) : "v"(lo), "v"(hi)); return r; }
; #define GAS __attribute__((address_space(1)))
;     __device__ __forceinline__ void operator()(const f32x4 (&acc)[2][2][4][2], const pg8::Unit& u, int wr, int wc, int fr, int fq) const {
;     ...
;             for (int m = 0; m < 4; ++m) {
;                 const int row = row0 + 128 * ai + 16 * m;
;                 const float rstd = __builtin_amdgcn_rsqf(rs[ai][m] * (1.0f / DM) + EPSF);
;                 f32x4 o[2];
; #pragma unroll
;                 for (int n = 0; n < 2; ++n) {
;                     const f32x4 g = acc[ai][0][m][n] * rstd + sh[0][n], uu = acc[ai][1][m][n] * rstd + sh[1][n];
; #pragma unroll
;                     for (int h = 0; h < 2; ++h) {
;                         const f32x2 g2 = {g[2 * h], g[2 * h + 1]}, u2 = {uu[2 * h], uu[2 * h + 1]};
;                         const f32x2 t = g2 * (-1.4426950408889634f);
;                         f32x2 e; e.x = __builtin_amdgcn_exp2f(t.x); e.y = __builtin_amdgcn_exp2f(t.y);
;                         const f32x2 d = e + 1.0f;
;                         f32x2 r; r.x = __builtin_amdgcn_rcpf(d.x); r.y = __builtin_amdgcn_rcpf(d.y);
;                         const f32x2 p = (g2 * u2) * r;
;                         o[n][2 * h] = p.x; o[n][2 * h + 1] = p.y;
;                     }
;                 }
;                 u32x4 w; w.x = cvt_pk_bf16(o[0][0], o[0][1]); w.y = cvt_pk_bf16(o[0][2], o[0][3]); w.z = cvt_pk_bf16(o[1][0], o[1][1]); w.w = cvt_pk_bf16(o[1][2], o[1][3]);
;                 *(GAS u32x4*)(act + (((size_t)u.pm * (FH / 64) + 2 * u.pn + (wc >> 1)) * 256 + (row - 256 * u.pm)) * 64 + 32 * (wc & 1) + 8 * fq) = w;
	v_exp_f32_e32 v127, v127
	v_pk_add_f32 v[132:133], v[132:133], 1.0 op_sel_hi:[1,0]
	v_pk_mul_f32 v[116:117], v[120:121], v[116:117]
	v_rcp_f32_e32 v132, v132
	v_pk_add_f32 v[126:127], v[126:127], 1.0 op_sel_hi:[1,0]
	v_rcp_f32_e32 v133, v133
	v_rcp_f32_e32 v126, v126
	v_rcp_f32_e32 v127, v127
	v_pk_mul_f32 v[122:123], v[122:123], v[132:133]
	v_pk_mul_f32 v[118:119], v[114:115], v[126:127]
	v_pk_mul_f32 v[114:115], v[120:121], s[18:19] op_sel_hi:[1,0]
	s_nop 0
	v_exp_f32_e32 v114, v114
	v_exp_f32_e32 v115, v115
	s_nop 0
	v_pk_add_f32 v[114:115], v[114:115], 1.0 op_sel_hi:[1,0]
	s_nop 0
	v_rcp_f32_e32 v114, v114
	v_rcp_f32_e32 v115, v115
	s_nop 0
	v_pk_mul_f32 v[120:121], v[116:117], v[114:115]
	v_cvt_pk_bf16_f32 v114, v122, v123
	v_cvt_pk_bf16_f32 v115, v124, v125
	v_cvt_pk_bf16_f32 v116, v118, v119
	v_lshl_add_u64 v[118:119], s[28:29], 0, v[158:159]
	v_lshl_add_u64 v[118:119], v[118:119], 0, s[30:31]
	v_lshl_add_u64 v[118:119], v[118:119], 0, v[178:179]
	v_cvt_pk_bf16_f32 v117, v120, v121
	global_store_dwordx4 v[118:119], v[114:117], off
	s_nop 1
	v_fmamk_f32 v114, v191, 0x3a800000, v233
	v_rsq_f32_e32 v114, v114
	s_nop 0
	v_pk_fma_f32 v[112:113], v[112:113], v[114:115], v[84:85] op_sel_hi:[1,0,1]
	v_pk_fma_f32 v[110:111], v[110:111], v[114:115], v[82:83] op_sel_hi:[1,0,1]
	v_pk_fma_f32 v[106:107], v[106:107], v[114:115], v[78:79] op_sel_hi:[1,0,1]
	v_pk_mul_f32 v[116:117], v[110:111], s[18:19] op_sel_hi:[1,0]
	v_pk_mul_f32 v[106:107], v[110:111], v[106:107]
	v_pk_mul_f32 v[110:111], v[112:113], s[18:19] op_sel_hi:[1,0]
	v_pk_fma_f32 v[108:109], v[108:109], v[114:115], v[80:81] op_sel_hi:[1,0,1]
	v_exp_f32_e32 v110, v110
	v_exp_f32_e32 v111, v111
	v_pk_mul_f32 v[108:109], v[112:113], v[108:109]
	v_pk_fma_f32 v[102:103], v[102:103], v[114:115], v[70:71] op_sel_hi:[1,0,1]
	v_pk_fma_f32 v[98:99], v[98:99], v[114:115], v[66:67] op_sel_hi:[1,0,1]
	v_pk_add_f32 v[110:111], v[110:111], 1.0 op_sel_hi:[1,0]
	v_pk_fma_f32 v[104:105], v[104:105], v[114:115], v[72:73] op_sel_hi:[1,0,1]
	v_rcp_f32_e32 v110, v110
	v_rcp_f32_e32 v111, v111
	v_pk_mul_f32 v[98:99], v[102:103], v[98:99]
	v_exp_f32_e32 v116, v116
	v_exp_f32_e32 v117, v117
	v_pk_mul_f32 v[108:109], v[108:109], v[110:111]
	v_pk_mul_f32 v[110:111], v[102:103], s[18:19] op_sel_hi:[1,0]
	v_pk_fma_f32 v[100:101], v[100:101], v[114:115], v[68:69] op_sel_hi:[1,0,1]
	v_exp_f32_e32 v110, v110
	v_exp_f32_e32 v111, v111
	v_pk_add_f32 v[116:117], v[116:117], 1.0 op_sel_hi:[1,0]
	v_pk_mul_f32 v[100:101], v[104:105], v[100:101]
	v_rcp_f32_e32 v116, v116
	v_pk_add_f32 v[110:111], v[110:111], 1.0 op_sel_hi:[1,0]
	v_rcp_f32_e32 v117, v117
	v_rcp_f32_e32 v110, v110
	v_rcp_f32_e32 v111, v111
	v_pk_mul_f32 v[106:107], v[106:107], v[116:117]
	v_pk_mul_f32 v[102:103], v[98:99], v[110:111]
	v_pk_mul_f32 v[98:99], v[104:105], s[18:19] op_sel_hi:[1,0]
	s_nop 0
	v_exp_f32_e32 v98, v98
	v_exp_f32_e32 v99, v99
	s_nop 0
	v_pk_add_f32 v[98:99], v[98:99], 1.0 op_sel_hi:[1,0]
	s_nop 0
	v_rcp_f32_e32 v98, v98
	v_rcp_f32_e32 v99, v99
	s_nop 0
	v_pk_mul_f32 v[104:105], v[100:101], v[98:99]
	v_cvt_pk_bf16_f32 v98, v106, v107
	v_cvt_pk_bf16_f32 v99, v108, v109
	v_cvt_pk_bf16_f32 v100, v102, v103
	v_lshl_add_u64 v[102:103], s[28:29], 0, v[160:161]
	v_lshl_add_u64 v[102:103], v[102:103], 0, s[30:31]
	v_lshl_add_u64 v[102:103], v[102:103], 0, v[178:179]
	v_cvt_pk_bf16_f32 v101, v104, v105
	global_store_dwordx4 v[102:103], v[98:101], off
	s_nop 1
	v_fmamk_f32 v98, v190, 0x3a800000, v233
	v_rsq_f32_e32 v98, v98
	s_nop 0
	v_pk_fma_f32 v[96:97], v[96:97], v[98:99], v[84:85] op_sel_hi:[1,0,1]
	v_pk_fma_f32 v[94:95], v[94:95], v[98:99], v[82:83] op_sel_hi:[1,0,1]
	v_pk_fma_f32 v[90:91], v[90:91], v[98:99], v[78:79] op_sel_hi:[1,0,1]
	v_pk_mul_f32 v[100:101], v[94:95], s[18:19] op_sel_hi:[1,0]
	v_pk_mul_f32 v[90:91], v[94:95], v[90:91]
	v_pk_mul_f32 v[94:95], v[96:97], s[18:19] op_sel_hi:[1,0]
	v_pk_fma_f32 v[92:93], v[92:93], v[98:99], v[80:81] op_sel_hi:[1,0,1]
	v_exp_f32_e32 v94, v94
	v_exp_f32_e32 v95, v95
	v_pk_mul_f32 v[92:93], v[96:97], v[92:93]
	v_pk_fma_f32 v[86:87], v[86:87], v[98:99], v[70:71] op_sel_hi:[1,0,1]
	v_pk_fma_f32 v[74:75], v[74:75], v[98:99], v[66:67] op_sel_hi:[1,0,1]
	v_pk_add_f32 v[94:95], v[94:95], 1.0 op_sel_hi:[1,0]
	v_pk_fma_f32 v[88:89], v[88:89], v[98:99], v[72:73] op_sel_hi:[1,0,1]
	v_rcp_f32_e32 v94, v94
	v_rcp_f32_e32 v95, v95
	v_pk_mul_f32 v[74:75], v[86:87], v[74:75]
	v_exp_f32_e32 v100, v100
	v_exp_f32_e32 v101, v101
	v_pk_mul_f32 v[92:93], v[92:93], v[94:95]
	v_pk_mul_f32 v[94:95], v[86:87], s[18:19] op_sel_hi:[1,0]
	v_pk_fma_f32 v[76:77], v[76:77], v[98:99], v[68:69] op_sel_hi:[1,0,1]
	v_exp_f32_e32 v94, v94
	v_exp_f32_e32 v95, v95
	v_pk_add_f32 v[100:101], v[100:101], 1.0 op_sel_hi:[1,0]
	v_pk_mul_f32 v[76:77], v[88:89], v[76:77]
	v_rcp_f32_e32 v100, v100
	v_pk_add_f32 v[94:95], v[94:95], 1.0 op_sel_hi:[1,0]
	v_rcp_f32_e32 v101, v101
	v_rcp_f32_e32 v94, v94
	v_rcp_f32_e32 v95, v95
	v_pk_mul_f32 v[90:91], v[90:91], v[100:101]
	v_pk_mul_f32 v[86:87], v[74:75], v[94:95]
	v_pk_mul_f32 v[74:75], v[88:89], s[18:19] op_sel_hi:[1,0]
	s_nop 0
	v_exp_f32_e32 v74, v74
	v_exp_f32_e32 v75, v75
	s_nop 0
	v_pk_add_f32 v[74:75], v[74:75], 1.0 op_sel_hi:[1,0]
	s_nop 0
	v_rcp_f32_e32 v74, v74
	v_rcp_f32_e32 v75, v75
	s_nop 0
	v_pk_mul_f32 v[88:89], v[76:77], v[74:75]
	v_cvt_pk_bf16_f32 v74, v90, v91
	v_cvt_pk_bf16_f32 v75, v92, v93
	v_cvt_pk_bf16_f32 v76, v86, v87
	v_lshl_add_u64 v[86:87], s[28:29], 0, v[162:163]
	v_lshl_add_u64 v[86:87], v[86:87], 0, s[30:31]
	v_lshl_add_u64 v[86:87], v[86:87], 0, v[178:179]
	v_cvt_pk_bf16_f32 v77, v88, v89
	global_store_dwordx4 v[86:87], v[74:77], off
	s_nop 1
; __device__ __forceinline__ unsigned cvt_pk_bf16(float lo, float hi) { unsigned r; asm volatile("v_cvt_pk_bf16_f32 %0, %1, %2" : "=v"(r) : "v"(lo), "v"(hi)); return r; }
; #define GAS __attribute__((address_space(1)))
;     __device__ __forceinline__ void operator()(const f32x4 (&acc)[2][2][4][2], const pg8::Unit& u, int wr, int wc, int fr, int fq) const {
;     ...
;             for (int m = 0; m < 4; ++m) {
;                 const int row = row0 + 128 * ai + 16 * m;
;                 const float rstd = __builtin_amdgcn_rsqf(rs[ai][m] * (1.0f / DM) + EPSF);
;                 f32x4 o[2];
; #pragma unroll
;                 for (int n = 0; n < 2; ++n) {
;                     const f32x4 g = acc[ai][0][m][n] * rstd + sh[0][n], uu = acc[ai][1][m][n] * rstd + sh[1][n];
; #pragma unroll
;                     for (int h = 0; h < 2; ++h) {
;                         const f32x2 g2 = {g[2 * h], g[2 * h + 1]}, u2 = {uu[2 * h], uu[2 * h + 1]};
;                         const f32x2 t = g2 * (-1.4426950408889634f);
;                         f32x2 e; e.x = __builtin_amdgcn_exp2f(t.x); e.y = __builtin_amdgcn_exp2f(t.y);
;                         const f32x2 d = e + 1.0f;
;                         f32x2 r; r.x = __builtin_amdgcn_rcpf(d.x); r.y = __builtin_amdgcn_rcpf(d.y);
;                         const f32x2 p = (g2 * u2) * r;
;                         o[n][2 * h] = p.x; o[n][2 * h + 1] = p.y;
;                     }
;                 }
;                 u32x4 w; w.x = cvt_pk_bf16(o[0][0], o[0][1]); w.y = cvt_pk_bf16(o[0][2], o[0][3]); w.z = cvt_pk_bf16(o[1][0], o[1][1]); w.w = cvt_pk_bf16(o[1][2], o[1][3]);
;                 *(GAS u32x4*)(act + (((size_t)u.pm * (FH / 64) + 2 * u.pn + (wc >> 1)) * 256 + (row - 256 * u.pm)) * 64 + 32 * (wc & 1) + 8 * fq) = w;
	v_fmamk_f32 v74, v189, 0x3a800000, v233
	v_rsq_f32_e32 v74, v74
	s_nop 0
	v_pk_fma_f32 v[64:65], v[64:65], v[74:75], v[84:85] op_sel_hi:[1,0,1]
	v_pk_fma_f32 v[62:63], v[62:63], v[74:75], v[82:83] op_sel_hi:[1,0,1]
	v_pk_fma_f32 v[58:59], v[58:59], v[74:75], v[78:79] op_sel_hi:[1,0,1]
	v_pk_mul_f32 v[76:77], v[62:63], s[18:19] op_sel_hi:[1,0]
	v_pk_mul_f32 v[58:59], v[62:63], v[58:59]
	v_pk_mul_f32 v[62:63], v[64:65], s[18:19] op_sel_hi:[1,0]
	v_pk_fma_f32 v[60:61], v[60:61], v[74:75], v[80:81] op_sel_hi:[1,0,1]
	v_exp_f32_e32 v62, v62
	v_exp_f32_e32 v63, v63
	v_pk_mul_f32 v[60:61], v[64:65], v[60:61]
	v_pk_fma_f32 v[54:55], v[54:55], v[74:75], v[70:71] op_sel_hi:[1,0,1]
	v_pk_fma_f32 v[50:51], v[50:51], v[74:75], v[66:67] op_sel_hi:[1,0,1]
	v_pk_add_f32 v[62:63], v[62:63], 1.0 op_sel_hi:[1,0]
	v_pk_fma_f32 v[56:57], v[56:57], v[74:75], v[72:73] op_sel_hi:[1,0,1]
	v_rcp_f32_e32 v62, v62
	v_rcp_f32_e32 v63, v63
	v_pk_mul_f32 v[50:51], v[54:55], v[50:51]
	v_exp_f32_e32 v76, v76
	v_exp_f32_e32 v77, v77
	v_pk_mul_f32 v[60:61], v[60:61], v[62:63]
	v_pk_mul_f32 v[62:63], v[54:55], s[18:19] op_sel_hi:[1,0]
	v_pk_fma_f32 v[52:53], v[52:53], v[74:75], v[68:69] op_sel_hi:[1,0,1]
	v_exp_f32_e32 v62, v62
	v_exp_f32_e32 v63, v63
	v_pk_add_f32 v[76:77], v[76:77], 1.0 op_sel_hi:[1,0]
	v_pk_mul_f32 v[52:53], v[56:57], v[52:53]
	v_rcp_f32_e32 v76, v76
	v_pk_add_f32 v[62:63], v[62:63], 1.0 op_sel_hi:[1,0]
	v_rcp_f32_e32 v77, v77
	v_rcp_f32_e32 v62, v62
	v_rcp_f32_e32 v63, v63
	v_pk_mul_f32 v[58:59], v[58:59], v[76:77]
	v_pk_mul_f32 v[54:55], v[50:51], v[62:63]
	v_pk_mul_f32 v[50:51], v[56:57], s[18:19] op_sel_hi:[1,0]
	s_nop 0
	v_exp_f32_e32 v50, v50
	v_exp_f32_e32 v51, v51
	s_nop 0
	v_pk_add_f32 v[50:51], v[50:51], 1.0 op_sel_hi:[1,0]
	s_nop 0
	v_rcp_f32_e32 v50, v50
	v_rcp_f32_e32 v51, v51
	s_nop 0
	v_pk_mul_f32 v[56:57], v[52:53], v[50:51]
	v_cvt_pk_bf16_f32 v50, v58, v59
	v_cvt_pk_bf16_f32 v51, v60, v61
	v_cvt_pk_bf16_f32 v52, v54, v55
	v_lshl_add_u64 v[54:55], s[28:29], 0, v[164:165]
	v_lshl_add_u64 v[54:55], v[54:55], 0, s[30:31]
	v_lshl_add_u64 v[54:55], v[54:55], 0, v[178:179]
	v_cvt_pk_bf16_f32 v53, v56, v57
	global_store_dwordx4 v[54:55], v[50:53], off
	s_nop 1
	v_fmamk_f32 v50, v188, 0x3a800000, v233
	v_rsq_f32_e32 v50, v50
	s_nop 0
	v_pk_fma_f32 v[48:49], v[48:49], v[50:51], v[84:85] op_sel_hi:[1,0,1]
	v_pk_fma_f32 v[46:47], v[46:47], v[50:51], v[82:83] op_sel_hi:[1,0,1]
	v_pk_fma_f32 v[42:43], v[42:43], v[50:51], v[78:79] op_sel_hi:[1,0,1]
	v_pk_mul_f32 v[52:53], v[46:47], s[18:19] op_sel_hi:[1,0]
	v_pk_mul_f32 v[42:43], v[46:47], v[42:43]
	v_pk_mul_f32 v[46:47], v[48:49], s[18:19] op_sel_hi:[1,0]
	v_pk_fma_f32 v[44:45], v[44:45], v[50:51], v[80:81] op_sel_hi:[1,0,1]
	v_exp_f32_e32 v46, v46
	v_exp_f32_e32 v47, v47
	v_pk_mul_f32 v[44:45], v[48:49], v[44:45]
	v_pk_fma_f32 v[38:39], v[38:39], v[50:51], v[70:71] op_sel_hi:[1,0,1]
	v_pk_fma_f32 v[34:35], v[34:35], v[50:51], v[66:67] op_sel_hi:[1,0,1]
	v_pk_add_f32 v[46:47], v[46:47], 1.0 op_sel_hi:[1,0]
	v_pk_fma_f32 v[40:41], v[40:41], v[50:51], v[72:73] op_sel_hi:[1,0,1]
	v_rcp_f32_e32 v46, v46
	v_rcp_f32_e32 v47, v47
	v_pk_mul_f32 v[34:35], v[38:39], v[34:35]
	v_exp_f32_e32 v52, v52
	v_exp_f32_e32 v53, v53
	v_pk_mul_f32 v[44:45], v[44:45], v[46:47]
	v_pk_mul_f32 v[46:47], v[38:39], s[18:19] op_sel_hi:[1,0]
	v_pk_fma_f32 v[36:37], v[36:37], v[50:51], v[68:69] op_sel_hi:[1,0,1]
	v_exp_f32_e32 v46, v46
	v_exp_f32_e32 v47, v47
	v_pk_add_f32 v[52:53], v[52:53], 1.0 op_sel_hi:[1,0]
	v_pk_mul_f32 v[36:37], v[40:41], v[36:37]
	v_rcp_f32_e32 v52, v52
	v_pk_add_f32 v[46:47], v[46:47], 1.0 op_sel_hi:[1,0]
	v_rcp_f32_e32 v53, v53
	v_rcp_f32_e32 v46, v46
	v_rcp_f32_e32 v47, v47
	v_pk_mul_f32 v[42:43], v[42:43], v[52:53]
	v_pk_mul_f32 v[38:39], v[34:35], v[46:47]
	v_pk_mul_f32 v[34:35], v[40:41], s[18:19] op_sel_hi:[1,0]
	s_nop 0
	v_exp_f32_e32 v34, v34
	v_exp_f32_e32 v35, v35
	s_nop 0
	v_pk_add_f32 v[34:35], v[34:35], 1.0 op_sel_hi:[1,0]
	s_nop 0
	v_rcp_f32_e32 v34, v34
	v_rcp_f32_e32 v35, v35
	s_nop 0
	v_pk_mul_f32 v[40:41], v[36:37], v[34:35]
	v_cvt_pk_bf16_f32 v34, v42, v43
	v_cvt_pk_bf16_f32 v35, v44, v45
	v_cvt_pk_bf16_f32 v36, v38, v39
	v_lshl_add_u64 v[38:39], s[28:29], 0, v[166:167]
	v_lshl_add_u64 v[38:39], v[38:39], 0, s[30:31]
	v_lshl_add_u64 v[38:39], v[38:39], 0, v[178:179]
	v_cvt_pk_bf16_f32 v37, v40, v41
	global_store_dwordx4 v[38:39], v[34:37], off
	s_nop 1
	v_fmamk_f32 v34, v187, 0x3a800000, v233
; __device__ __forceinline__ unsigned cvt_pk_bf16(float lo, float hi) { unsigned r; asm volatile("v_cvt_pk_bf16_f32 %0, %1, %2" : "=v"(r) : "v"(lo), "v"(hi)); return r; }
; #define GAS __attribute__((address_space(1)))
;     __device__ __forceinline__ void operator()(const f32x4 (&acc)[2][2][4][2], const pg8::Unit& u, int wr, int wc, int fr, int fq) const {
;     ...
;             for (int m = 0; m < 4; ++m) {
;                 const int row = row0 + 128 * ai + 16 * m;
;                 const float rstd = __builtin_amdgcn_rsqf(rs[ai][m] * (1.0f / DM) + EPSF);
;                 f32x4 o[2];
; #pragma unroll
;                 for (int n = 0; n < 2; ++n) {
;                     const f32x4 g = acc[ai][0][m][n] * rstd + sh[0][n], uu = acc[ai][1][m][n] * rstd + sh[1][n];
; #pragma unroll
;                     for (int h = 0; h < 2; ++h) {
;                         const f32x2 g2 = {g[2 * h], g[2 * h + 1]}, u2 = {uu[2 * h], uu[2 * h + 1]};
;                         const f32x2 t = g2 * (-1.4426950408889634f);
;                         f32x2 e; e.x = __builtin_amdgcn_exp2f(t.x); e.y = __builtin_amdgcn_exp2f(t.y);
;                         const f32x2 d = e + 1.0f;
;                         f32x2 r; r.x = __builtin_amdgcn_rcpf(d.x); r.y = __builtin_amdgcn_rcpf(d.y);
;                         const f32x2 p = (g2 * u2) * r;
;                         o[n][2 * h] = p.x; o[n][2 * h + 1] = p.y;
;                     }
;                 }
;                 u32x4 w; w.x = cvt_pk_bf16(o[0][0], o[0][1]); w.y = cvt_pk_bf16(o[0][2], o[0][3]); w.z = cvt_pk_bf16(o[1][0], o[1][1]); w.w = cvt_pk_bf16(o[1][2], o[1][3]);
;                 *(GAS u32x4*)(act + (((size_t)u.pm * (FH / 64) + 2 * u.pn + (wc >> 1)) * 256 + (row - 256 * u.pm)) * 64 + 32 * (wc & 1) + 8 * fq) = w;
	v_rsq_f32_e32 v34, v34
	s_nop 0
	v_pk_fma_f32 v[32:33], v[32:33], v[34:35], v[84:85] op_sel_hi:[1,0,1]
	v_pk_fma_f32 v[30:31], v[30:31], v[34:35], v[82:83] op_sel_hi:[1,0,1]
	v_pk_fma_f32 v[26:27], v[26:27], v[34:35], v[78:79] op_sel_hi:[1,0,1]
	v_pk_mul_f32 v[36:37], v[30:31], s[18:19] op_sel_hi:[1,0]
	v_pk_mul_f32 v[26:27], v[30:31], v[26:27]
	v_pk_mul_f32 v[30:31], v[32:33], s[18:19] op_sel_hi:[1,0]
	v_pk_fma_f32 v[28:29], v[28:29], v[34:35], v[80:81] op_sel_hi:[1,0,1]
	v_exp_f32_e32 v30, v30
	v_exp_f32_e32 v31, v31
	v_pk_mul_f32 v[28:29], v[32:33], v[28:29]
	v_pk_fma_f32 v[22:23], v[22:23], v[34:35], v[70:71] op_sel_hi:[1,0,1]
	v_pk_fma_f32 v[18:19], v[18:19], v[34:35], v[66:67] op_sel_hi:[1,0,1]
	v_pk_add_f32 v[30:31], v[30:31], 1.0 op_sel_hi:[1,0]
	v_pk_fma_f32 v[24:25], v[24:25], v[34:35], v[72:73] op_sel_hi:[1,0,1]
	v_rcp_f32_e32 v30, v30
	v_rcp_f32_e32 v31, v31
	v_pk_mul_f32 v[18:19], v[22:23], v[18:19]
	v_exp_f32_e32 v36, v36
	v_exp_f32_e32 v37, v37
	v_pk_mul_f32 v[28:29], v[28:29], v[30:31]
	v_pk_mul_f32 v[30:31], v[22:23], s[18:19] op_sel_hi:[1,0]
	v_pk_fma_f32 v[20:21], v[20:21], v[34:35], v[68:69] op_sel_hi:[1,0,1]
	v_exp_f32_e32 v30, v30
	v_exp_f32_e32 v31, v31
	v_pk_add_f32 v[36:37], v[36:37], 1.0 op_sel_hi:[1,0]
	v_pk_mul_f32 v[20:21], v[24:25], v[20:21]
	v_rcp_f32_e32 v36, v36
	v_pk_add_f32 v[30:31], v[30:31], 1.0 op_sel_hi:[1,0]
	v_rcp_f32_e32 v37, v37
	v_rcp_f32_e32 v30, v30
	v_rcp_f32_e32 v31, v31
	v_pk_mul_f32 v[26:27], v[26:27], v[36:37]
	v_pk_mul_f32 v[22:23], v[18:19], v[30:31]
	v_pk_mul_f32 v[18:19], v[24:25], s[18:19] op_sel_hi:[1,0]
	s_nop 0
	v_exp_f32_e32 v18, v18
	v_exp_f32_e32 v19, v19
	s_nop 0
	v_pk_add_f32 v[18:19], v[18:19], 1.0 op_sel_hi:[1,0]
	s_nop 0
	v_rcp_f32_e32 v18, v18
	v_rcp_f32_e32 v19, v19
	s_nop 0
	v_pk_mul_f32 v[24:25], v[20:21], v[18:19]
	v_cvt_pk_bf16_f32 v18, v26, v27
	v_cvt_pk_bf16_f32 v19, v28, v29
	v_cvt_pk_bf16_f32 v20, v22, v23
	v_lshl_add_u64 v[22:23], s[28:29], 0, v[168:169]
	v_lshl_add_u64 v[22:23], v[22:23], 0, s[30:31]
	v_lshl_add_u64 v[22:23], v[22:23], 0, v[178:179]
	v_cvt_pk_bf16_f32 v21, v24, v25
	global_store_dwordx4 v[22:23], v[18:21], off
	s_nop 1
	v_fmamk_f32 v18, v186, 0x3a800000, v233
	v_rsq_f32_e32 v18, v18
	s_nop 0
	v_pk_fma_f32 v[16:17], v[16:17], v[18:19], v[84:85] op_sel_hi:[1,0,1]
	v_pk_fma_f32 v[14:15], v[14:15], v[18:19], v[82:83] op_sel_hi:[1,0,1]
	v_pk_fma_f32 v[10:11], v[10:11], v[18:19], v[78:79] op_sel_hi:[1,0,1]
	v_pk_mul_f32 v[20:21], v[14:15], s[18:19] op_sel_hi:[1,0]
	v_pk_mul_f32 v[10:11], v[14:15], v[10:11]
	v_pk_mul_f32 v[14:15], v[16:17], s[18:19] op_sel_hi:[1,0]
	v_pk_fma_f32 v[12:13], v[12:13], v[18:19], v[80:81] op_sel_hi:[1,0,1]
	v_exp_f32_e32 v14, v14
	v_exp_f32_e32 v15, v15
	v_pk_mul_f32 v[12:13], v[16:17], v[12:13]
	v_pk_fma_f32 v[6:7], v[6:7], v[18:19], v[70:71] op_sel_hi:[1,0,1]
	v_pk_fma_f32 v[2:3], v[2:3], v[18:19], v[66:67] op_sel_hi:[1,0,1]
	v_pk_add_f32 v[14:15], v[14:15], 1.0 op_sel_hi:[1,0]
	v_pk_fma_f32 v[8:9], v[8:9], v[18:19], v[72:73] op_sel_hi:[1,0,1]
	v_rcp_f32_e32 v14, v14
	v_rcp_f32_e32 v15, v15
	v_pk_mul_f32 v[2:3], v[6:7], v[2:3]
	v_exp_f32_e32 v20, v20
	v_exp_f32_e32 v21, v21
	v_pk_mul_f32 v[12:13], v[12:13], v[14:15]
	v_pk_mul_f32 v[14:15], v[6:7], s[18:19] op_sel_hi:[1,0]
	v_pk_fma_f32 v[4:5], v[4:5], v[18:19], v[68:69] op_sel_hi:[1,0,1]
	v_exp_f32_e32 v14, v14
	v_exp_f32_e32 v15, v15
	v_pk_add_f32 v[20:21], v[20:21], 1.0 op_sel_hi:[1,0]
	v_pk_mul_f32 v[4:5], v[8:9], v[4:5]
	v_rcp_f32_e32 v20, v20
	v_pk_add_f32 v[14:15], v[14:15], 1.0 op_sel_hi:[1,0]
	v_rcp_f32_e32 v21, v21
	v_rcp_f32_e32 v14, v14
	v_rcp_f32_e32 v15, v15
	v_pk_mul_f32 v[10:11], v[10:11], v[20:21]
	v_pk_mul_f32 v[6:7], v[2:3], v[14:15]
	v_pk_mul_f32 v[2:3], v[8:9], s[18:19] op_sel_hi:[1,0]
	s_nop 0
	v_exp_f32_e32 v2, v2
	v_exp_f32_e32 v3, v3
	s_nop 0
	v_pk_add_f32 v[2:3], v[2:3], 1.0 op_sel_hi:[1,0]
	s_nop 0
	v_rcp_f32_e32 v2, v2
	v_rcp_f32_e32 v3, v3
	s_nop 0
	v_pk_mul_f32 v[8:9], v[4:5], v[2:3]
	v_cvt_pk_bf16_f32 v2, v10, v11
	v_cvt_pk_bf16_f32 v3, v12, v13
	v_cvt_pk_bf16_f32 v4, v6, v7
	v_lshl_add_u64 v[6:7], s[28:29], 0, v[170:171]
	v_lshl_add_u64 v[6:7], v[6:7], 0, s[30:31]
	v_lshl_add_u64 v[6:7], v[6:7], 0, v[178:179]
	s_mov_b64 s[28:29], -1
	v_cvt_pk_bf16_f32 v5, v8, v9
	global_store_dwordx4 v[6:7], v[2:5], off
	s_cbranch_vccnz .LBB0_162
	s_andn2_b64 vcc, exec, s[2:3]
	s_cbranch_vccnz .LBB0_161
	s_barrier
	s_branch .LBB0_161

; #define GAS __attribute__((address_space(1)))
; __device__ __forceinline__ void shw_reduce(GAS unsigned char* ws, int l, int gt, int NGT) {
;     const GAS float* shp = (const GAS float*)(ws + WS_SHP) + (size_t)l * 16 * SHW_N;
;     for (int i = gt; i < SHW_N; i += NGT) { float a = 0.f;
; #pragma unroll
;         for (int kb = 0; kb < 16; ++kb) a += shp[(size_t)kb * SHW_N + i];
;         if (i < INP) ((GAS float*)(ws + WS_SHWIN))[l * INP + i] = a; else ((GAS float*)(ws + WS_SHWGU))[l * GU + i - INP] = a; }
.LBB0_535:
	s_movk_i32 s3, 0xbff
	v_add_co_u32_e32 v6, vcc, 0xfff80800, v4
	s_nop 1
	v_addc_co_u32_e32 v7, vcc, -1, v5, vcc
	global_load_dword v8, v[6:7], off
	v_add_co_u32_e32 v6, vcc, 0xfff89000, v4
	s_nop 1
	v_addc_co_u32_e32 v7, vcc, -1, v5, vcc
	global_load_dword v9, v[6:7], off
	v_add_co_u32_e32 v6, vcc, 0xfff91800, v4
	s_nop 1
	v_addc_co_u32_e32 v7, vcc, -1, v5, vcc
	global_load_dword v10, v[6:7], off
	v_add_co_u32_e32 v6, vcc, 0xfff9a000, v4
	s_nop 1
	v_addc_co_u32_e32 v7, vcc, -1, v5, vcc
	global_load_dword v11, v[6:7], off
	v_add_co_u32_e32 v6, vcc, 0xfffa2800, v4
	s_nop 1
	v_addc_co_u32_e32 v7, vcc, -1, v5, vcc
	global_load_dword v12, v[6:7], off
	v_add_co_u32_e32 v6, vcc, 0xfffab000, v4
	s_nop 1
	v_addc_co_u32_e32 v7, vcc, -1, v5, vcc
	global_load_dword v13, v[6:7], off
	v_add_co_u32_e32 v6, vcc, 0xfffb3800, v4
	s_nop 1
	v_addc_co_u32_e32 v7, vcc, -1, v5, vcc
	global_load_dword v14, v[6:7], off
	v_add_co_u32_e32 v6, vcc, 0xfffbc000, v4
	s_nop 1
	v_addc_co_u32_e32 v7, vcc, -1, v5, vcc
	global_load_dword v15, v[6:7], off
	v_add_co_u32_e32 v6, vcc, 0xfffc4800, v4
	s_nop 1
	v_addc_co_u32_e32 v7, vcc, -1, v5, vcc
	global_load_dword v16, v[6:7], off
	v_add_co_u32_e32 v6, vcc, 0xfffcd000, v4
	s_nop 1
	v_addc_co_u32_e32 v7, vcc, -1, v5, vcc
	global_load_dword v17, v[6:7], off
	v_add_co_u32_e32 v6, vcc, 0xfffd5800, v4
	s_nop 1
	v_addc_co_u32_e32 v7, vcc, -1, v5, vcc
	global_load_dword v18, v[6:7], off
	v_add_co_u32_e32 v6, vcc, 0xfffde000, v4
	s_nop 1
	v_addc_co_u32_e32 v7, vcc, -1, v5, vcc
	global_load_dword v19, v[6:7], off
	v_add_co_u32_e32 v6, vcc, 0xfffe6800, v4
	s_nop 1
	v_addc_co_u32_e32 v7, vcc, -1, v5, vcc
	global_load_dword v20, v[6:7], off
	v_add_co_u32_e32 v6, vcc, 0xfffef000, v4
	s_nop 1
	v_addc_co_u32_e32 v7, vcc, -1, v5, vcc
	global_load_dword v21, v[6:7], off
	v_add_co_u32_e32 v6, vcc, 0xffff7800, v4
	s_nop 1
	v_addc_co_u32_e32 v7, vcc, -1, v5, vcc
	global_load_dword v22, v[6:7], off
	global_load_dword v23, v[4:5], off
	s_waitcnt vmcnt(15)
	v_add_f32_e32 v1, 0, v8
	s_waitcnt vmcnt(14)
	v_add_f32_e32 v1, v1, v9
	s_waitcnt vmcnt(13)
	v_add_f32_e32 v1, v1, v10
	s_waitcnt vmcnt(12)
	v_add_f32_e32 v1, v1, v11
	s_waitcnt vmcnt(11)
	v_add_f32_e32 v1, v1, v12
	s_waitcnt vmcnt(10)
	v_add_f32_e32 v1, v1, v13
	s_waitcnt vmcnt(9)
	v_add_f32_e32 v1, v1, v14
	s_waitcnt vmcnt(8)
	v_add_f32_e32 v1, v1, v15
	s_waitcnt vmcnt(7)
	v_add_f32_e32 v1, v1, v16
	s_waitcnt vmcnt(6)
	v_add_f32_e32 v1, v1, v17
	s_waitcnt vmcnt(5)
	v_add_f32_e32 v1, v1, v18
	s_waitcnt vmcnt(4)
	v_add_f32_e32 v1, v1, v19
	s_waitcnt vmcnt(3)
	v_add_f32_e32 v1, v1, v20
	s_waitcnt vmcnt(2)
	v_add_f32_e32 v1, v1, v21
	s_waitcnt vmcnt(1)
	v_add_f32_e32 v1, v1, v22
	v_cmp_lt_i32_e32 vcc, s3, v2
	s_waitcnt vmcnt(0)
	v_add_f32_e32 v1, v1, v23
	s_and_saveexec_b64 s[10:11], vcc
	s_xor_b64 s[10:11], exec, s[10:11]
	s_cbranch_execz .LBB0_537
	v_add_u32_e32 v178, s12, v2
	v_lshl_add_u64 v[6:7], v[178:179], 2, s[22:23]
	v_add_co_u32_e32 v6, vcc, 0x11b7d000, v6
	s_nop 1
	v_addc_co_u32_e32 v7, vcc, 0, v7, vcc
	global_store_dword v[6:7], v1, off
